# up-proj epilogue: conv taps fused into DPP fmac (hand-generated main section, constants read twice instead of 16x), conv tap global loads hoisted before K-loop so epilogue no longer drains vmcnt(0)
# speedup vs baseline: 1.0673x; 1.0109x over previous
.LBB0_222:
	s_ashr_i32 s51, s50, 31
	s_lshl_b64 s[10:11], s[50:51], 19
	v_readlane_b32 s30, v253, 38
	v_readlane_b32 s31, v253, 39
	s_add_u32 s54, s30, s10
	s_addc_u32 s55, s31, s11
	s_and_b64 s[0:1], s[0:1], exec
	s_cselect_b32 s29, s55, s9
	s_cselect_b32 s30, s54, s8
	s_add_u32 s31, s8, 0x100
	v_mov_b32_e32 v0, 0
	s_addc_u32 s33, s9, 0
	s_mov_b32 s34, -2
	v_mov_b32_e32 v1, v0
	v_mov_b32_e32 v2, v0
	v_mov_b32_e32 v3, v0
	v_mov_b32_e32 v8, v0
	v_mov_b32_e32 v9, v0
	v_mov_b32_e32 v10, v0
	v_mov_b32_e32 v11, v0
	v_mov_b32_e32 v16, v0
	v_mov_b32_e32 v17, v0
	v_mov_b32_e32 v18, v0
	v_mov_b32_e32 v19, v0
	v_mov_b32_e32 v24, v0
	v_mov_b32_e32 v25, v0
	v_mov_b32_e32 v26, v0
	v_mov_b32_e32 v27, v0
	v_mov_b32_e32 v36, v0
	v_mov_b32_e32 v37, v0
	v_mov_b32_e32 v38, v0
	v_mov_b32_e32 v39, v0
	v_mov_b32_e32 v52, v0
	v_mov_b32_e32 v53, v0
	v_mov_b32_e32 v54, v0
	v_mov_b32_e32 v55, v0
	v_mov_b32_e32 v40, v0
	v_mov_b32_e32 v41, v0
	v_mov_b32_e32 v42, v0
	v_mov_b32_e32 v43, v0
	v_mov_b32_e32 v56, v0
	v_mov_b32_e32 v57, v0
	v_mov_b32_e32 v58, v0
	v_mov_b32_e32 v59, v0
	v_mov_b32_e32 v4, v0
	v_mov_b32_e32 v5, v0
	v_mov_b32_e32 v6, v0
	v_mov_b32_e32 v7, v0
	v_mov_b32_e32 v12, v0
	v_mov_b32_e32 v13, v0
	v_mov_b32_e32 v14, v0
	v_mov_b32_e32 v15, v0
	v_mov_b32_e32 v20, v0
	v_mov_b32_e32 v21, v0
	v_mov_b32_e32 v22, v0
	v_mov_b32_e32 v23, v0
	v_mov_b32_e32 v32, v0
	v_mov_b32_e32 v33, v0
	v_mov_b32_e32 v34, v0
	v_mov_b32_e32 v35, v0
	s_waitcnt vmcnt(0)
	v_mov_b32_e32 v44, v0
	v_mov_b32_e32 v45, v0
	v_mov_b32_e32 v46, v0
	v_mov_b32_e32 v47, v0
	v_mov_b32_e32 v60, v0
	v_mov_b32_e32 v61, v0
	v_mov_b32_e32 v62, v0
	v_mov_b32_e32 v63, v0
	v_mov_b32_e32 v48, v0
	v_mov_b32_e32 v49, v0
	v_mov_b32_e32 v50, v0
	v_mov_b32_e32 v51, v0
	v_mov_b32_e32 v64, v0
	v_mov_b32_e32 v65, v0
	v_mov_b32_e32 v66, v0
	v_mov_b32_e32 v67, v0
	v_mov_b32_e32 v68, v0
	v_mov_b32_e32 v69, v0
	v_mov_b32_e32 v70, v0
	v_mov_b32_e32 v71, v0
	v_mov_b32_e32 v76, v0
	v_mov_b32_e32 v77, v0
	v_mov_b32_e32 v78, v0
	v_mov_b32_e32 v79, v0
	v_mov_b32_e32 v84, v0
	v_mov_b32_e32 v85, v0
	v_mov_b32_e32 v86, v0
	v_mov_b32_e32 v87, v0
	v_mov_b32_e32 v92, v0
	v_mov_b32_e32 v93, v0
	v_mov_b32_e32 v94, v0
	v_mov_b32_e32 v95, v0
	v_mov_b32_e32 v100, v0
	v_mov_b32_e32 v101, v0
	v_mov_b32_e32 v102, v0
	v_mov_b32_e32 v103, v0
	v_mov_b32_e32 v116, v0
	v_mov_b32_e32 v117, v0
	v_mov_b32_e32 v118, v0
	v_mov_b32_e32 v119, v0
	v_mov_b32_e32 v104, v0
	v_mov_b32_e32 v105, v0
	v_mov_b32_e32 v106, v0
	v_mov_b32_e32 v107, v0
	v_mov_b32_e32 v120, v0
	v_mov_b32_e32 v121, v0
	v_mov_b32_e32 v122, v0
	v_mov_b32_e32 v123, v0
	v_mov_b32_e32 v72, v0
	v_mov_b32_e32 v73, v0
	v_mov_b32_e32 v74, v0
	v_mov_b32_e32 v75, v0
	v_mov_b32_e32 v80, v0
	v_mov_b32_e32 v81, v0
	v_mov_b32_e32 v82, v0
	v_mov_b32_e32 v83, v0
	v_mov_b32_e32 v88, v0
	v_mov_b32_e32 v89, v0
	v_mov_b32_e32 v90, v0
	v_mov_b32_e32 v91, v0
	v_mov_b32_e32 v96, v0
	v_mov_b32_e32 v97, v0
	v_mov_b32_e32 v98, v0
	v_mov_b32_e32 v99, v0
	v_mov_b32_e32 v108, v0
	v_mov_b32_e32 v109, v0
	v_mov_b32_e32 v110, v0
	v_mov_b32_e32 v111, v0
	v_mov_b32_e32 v124, v0
	v_mov_b32_e32 v125, v0
	v_mov_b32_e32 v126, v0
	v_mov_b32_e32 v127, v0
	v_mov_b32_e32 v112, v0
	v_mov_b32_e32 v113, v0
	v_mov_b32_e32 v114, v0
	v_mov_b32_e32 v115, v0
	v_mov_b32_e32 v128, v0
	v_mov_b32_e32 v129, v0
	v_mov_b32_e32 v130, v0
	v_mov_b32_e32 v131, v0
	v_lshlrev_b32_e32 v244, 4, v169
	v_add3_u32 v246, s21, v168, v244
	v_bfe_i32 v244, v246, 7, 1
	v_and_b32_e32 v244, 0xb00, v244
	s_lshl_b32 s0, s28, 7
	v_add_u32_e32 v244, s0, v244
	s_movk_i32 s0, 0x7f
	v_and_or_b32 v244, v246, s0, v244
	v_ashrrev_i32_e32 v248, 8, v246
	v_mul_u32_u24_e32 v249, 0x1600, v248
	v_add_u32_e32 v249, v249, v244
	v_ashrrev_i32_e32 v245, 31, v244
	v_lshl_add_u64 v[246:247], v[244:245], 2, s[46:47]
	v_mov_b32_e32 v244, v249
	v_mov_b32_e32 v245, 0
	v_lshl_add_u64 v[244:245], v[244:245], 2, s[6:7]
	v_cmp_gt_i32_e32 vcc, 3, v248
	v_add_u32_e32 v249, 0x2c00, v249
	v_cmp_gt_i32_e64 s[0:1], 1, v248
	v_cndmask_b32_e32 v244, v246, v244, vcc
	v_cndmask_b32_e32 v245, v247, v245, vcc
	v_mov_b32_e32 v248, v249
	v_mov_b32_e32 v249, 0
	v_lshl_add_u64 v[248:249], v[248:249], 2, s[6:7]
	v_cndmask_b32_e64 v248, v246, v248, s[0:1]
	v_cndmask_b32_e64 v249, v247, v249, s[0:1]
	global_load_dword v244, v[244:245], off
	global_load_dword v245, v[248:249], off
	s_mov_b64 s[40:41], 0x80

.LBB0_226:
	v_mov_b32_e32 v138, v168
	v_mov_b32_e32 v132, v169
	s_lshl_b32 s8, s28, 7
	v_lshlrev_b32_e32 v139, 3, v132
	v_lshlrev_b32_e32 v132, 4, v132
	v_add3_u32 v156, s21, v138, v132
	v_bfe_i32 v132, v156, 7, 1
	v_and_b32_e32 v132, 0xb00, v132
	v_add_u32_e32 v132, s8, v132
	s_movk_i32 s0, 0x7f
	v_and_or_b32 v132, v156, s0, v132
	v_ashrrev_i32_e32 v133, 31, v132
	v_lshl_add_u64 v[134:135], v[132:133], 2, s[46:47]
	v_ashrrev_i32_e32 v133, 8, v156
	s_movk_i32 s0, 0x1600
	v_mad_i32_i24 v136, v133, s0, v132
	v_ashrrev_i32_e32 v137, 31, v136
	v_cmp_gt_i32_e32 vcc, 3, v133
	v_lshl_add_u64 v[136:137], v[136:137], 2, s[6:7]
	v_lshl_add_u32 v133, v156, 2, 0
	v_cndmask_b32_e32 v137, v135, v137, vcc
	v_cndmask_b32_e32 v136, v134, v136, vcc
	s_nop 0
	v_add_u32_e32 v137, 0x20000, v133
	v_add_u32_e32 v133, 0x200, v156
	v_ashrrev_i32_e32 v133, 8, v133
	v_mad_i32_i24 v132, v133, s0, v132
	v_cmp_gt_i32_e32 vcc, 3, v133
	v_ashrrev_i32_e32 v133, 31, v132
	v_lshl_add_u64 v[132:133], v[132:133], 2, s[6:7]
	v_cndmask_b32_e32 v133, v135, v133, vcc
	v_cndmask_b32_e32 v132, v134, v132, vcc
	s_nop 0
	s_lshl_b32 s0, s28, 8
	s_lshl_b32 s9, s27, 4
	s_or_b32 s0, s0, s18
	s_add_i32 s9, s9, s22
	v_add_u32_e32 v133, s9, v138
	v_cmp_lt_i32_e64 s[44:45], 1, v138
	v_cmp_gt_i32_e32 vcc, 2, v138
	s_nop 0
	ds_write2st64_b32 v137, v244, v245 offset1:8
	v_add_u32_e32 v132, s0, v139
	s_movk_i32 s0, 0x5800
	v_mad_i64_i32 v[134:135], s[0:1], v133, s0, 0
	s_waitcnt lgkmcnt(0)
	s_barrier
	v_readlane_b32 s0, v250, 10
	v_readlane_b32 s1, v250, 11
	v_ashrrev_i32_e32 v133, 31, v132
	s_nop 0
	v_lshl_add_u64 v[134:135], s[0:1], 0, v[134:135]
	s_and_saveexec_b64 s[0:1], vcc
	v_readlane_b32 s34, v254, 58
	v_readlane_b32 s35, v254, 59
	s_cbranch_execz .LBB0_228
	v_lshl_add_u64 v[136:137], v[132:133], 2, v[134:135]
	global_store_dwordx4 v[136:137], v[128:131], off

.LBB0_247:
	s_or_b64 exec, exec, s[2:3]
	v_cmp_lt_i32_e64 s[40:41], 13, v138
	v_cmp_eq_u32_e64 s[42:43], 15, v138
	s_lshl_b32 s0, s27, 8
	s_add_i32 s0, s0, s17
	v_add_u32_e32 v164, s0, v138
	v_mul_u32_u24_e32 v164, 0x3080, v164
	s_or_b32 s1, s8, s18
	v_add_u32_e32 v165, s1, v139
	v_lshl_add_u32 v164, v165, 1, v164
	v_lshlrev_b32_e32 v167, 2, v139
	v_add_u32_e32 v166, s23, v167
	v_add_u32_e32 v167, s24, v167
	ds_read_b128 v[202:205], v166 offset:0
	ds_read_b128 v[206:209], v166 offset:1024
	ds_read_b128 v[210:213], v166 offset:2048
	ds_read_b128 v[214:217], v166 offset:3072
	ds_read_b128 v[218:221], v167 offset:0
	ds_read_b128 v[222:225], v167 offset:1024
	ds_read_b128 v[226:229], v167 offset:2048
	ds_read_b128 v[230:233], v167 offset:3072
	s_waitcnt lgkmcnt(0)
	v_cndmask_b32_e64 v180, v128, v31, s[40:41]
	v_cndmask_b32_e64 v181, v128, v31, s[42:43]
	v_cndmask_b32_e64 v182, v129, v31, s[40:41]
	v_cndmask_b32_e64 v183, v129, v31, s[42:43]
	v_cndmask_b32_e64 v184, v130, v31, s[40:41]
	v_cndmask_b32_e64 v185, v130, v31, s[42:43]
	v_cndmask_b32_e64 v186, v131, v31, s[40:41]
	v_cndmask_b32_e64 v187, v131, v31, s[42:43]
	v_mov_b32_e32 v172, v214
	v_mov_b32_e32 v173, v215
	v_mov_b32_e32 v174, v216
	v_mov_b32_e32 v175, v217
	v_fmac_f32_dpp v172, v180, v202 row_ror:2 row_mask:0xf bank_mask:0xf
	v_fmac_f32_dpp v173, v182, v203 row_ror:2 row_mask:0xf bank_mask:0xf
	v_fmac_f32_dpp v174, v184, v204 row_ror:2 row_mask:0xf bank_mask:0xf
	v_fmac_f32_dpp v175, v186, v205 row_ror:2 row_mask:0xf bank_mask:0xf
	v_fmac_f32_dpp v172, v181, v206 row_ror:1 row_mask:0xf bank_mask:0xf
	v_fmac_f32_dpp v173, v183, v207 row_ror:1 row_mask:0xf bank_mask:0xf
	v_fmac_f32_dpp v174, v185, v208 row_ror:1 row_mask:0xf bank_mask:0xf
	v_fmac_f32_dpp v175, v187, v209 row_ror:1 row_mask:0xf bank_mask:0xf
	v_fmac_f32_e32 v172, v128, v210
	v_fmac_f32_e32 v173, v129, v211
	v_fmac_f32_e32 v174, v130, v212
	v_fmac_f32_e32 v175, v131, v213
	v_cndmask_b32_e64 v180, v120, v31, s[40:41]
	v_cndmask_b32_e64 v181, v120, v31, s[42:43]
	v_cndmask_b32_e64 v182, v121, v31, s[40:41]
	v_cndmask_b32_e64 v183, v121, v31, s[42:43]
	v_cndmask_b32_e64 v184, v122, v31, s[40:41]
	v_cndmask_b32_e64 v185, v122, v31, s[42:43]
	v_cndmask_b32_e64 v186, v123, v31, s[40:41]
	v_cndmask_b32_e64 v187, v123, v31, s[42:43]
	v_mov_b32_e32 v176, v230
	v_mov_b32_e32 v177, v231
	v_mov_b32_e32 v178, v232
	v_mov_b32_e32 v179, v233
	v_fmac_f32_dpp v176, v180, v218 row_ror:2 row_mask:0xf bank_mask:0xf
	v_fmac_f32_dpp v177, v182, v219 row_ror:2 row_mask:0xf bank_mask:0xf
	v_fmac_f32_dpp v178, v184, v220 row_ror:2 row_mask:0xf bank_mask:0xf
	v_fmac_f32_dpp v179, v186, v221 row_ror:2 row_mask:0xf bank_mask:0xf
	v_fmac_f32_dpp v176, v181, v222 row_ror:1 row_mask:0xf bank_mask:0xf
	v_fmac_f32_dpp v177, v183, v223 row_ror:1 row_mask:0xf bank_mask:0xf
	v_fmac_f32_dpp v178, v185, v224 row_ror:1 row_mask:0xf bank_mask:0xf
	v_fmac_f32_dpp v179, v187, v225 row_ror:1 row_mask:0xf bank_mask:0xf
	v_fmac_f32_e32 v176, v120, v226
	v_fmac_f32_e32 v177, v121, v227
	v_fmac_f32_e32 v178, v122, v228
	v_fmac_f32_e32 v179, v123, v229
	v_mul_f32_e32 v132, 0xbfb8aa3b, v172
	v_mul_f32_e32 v133, 0xbfb8aa3b, v173
	v_mul_f32_e32 v134, 0xbfb8aa3b, v174
	v_mul_f32_e32 v135, 0xbfb8aa3b, v175
	v_exp_f32_e32 v132, v132
	v_exp_f32_e32 v133, v133
	v_exp_f32_e32 v134, v134
	v_exp_f32_e32 v135, v135
	v_add_f32_e32 v132, 1.0, v132
	v_add_f32_e32 v133, 1.0, v133
	v_add_f32_e32 v134, 1.0, v134
	v_add_f32_e32 v135, 1.0, v135
	v_rcp_f32_e32 v132, v132
	v_rcp_f32_e32 v133, v133
	v_rcp_f32_e32 v134, v134
	v_rcp_f32_e32 v135, v135
	v_mul_f32_e32 v132, v172, v132
	v_mul_f32_e32 v133, v173, v133
	v_mul_f32_e32 v134, v174, v134
	v_mul_f32_e32 v135, v175, v135
	v_mul_f32_e32 v132, v132, v176
	v_mul_f32_e32 v133, v133, v177
	v_mul_f32_e32 v134, v134, v178
	v_mul_f32_e32 v135, v135, v179
	v_cvt_pk_bf16_f32 v136, v132, v133
	v_cvt_pk_bf16_f32 v137, v134, v135
	v_mov_b32_e32 v165, v164
	s_and_saveexec_b64 s[0:1], s[44:45]
	global_store_dwordx2 v165, v[136:137], s[34:35] offset:2048
	s_or_b64 exec, exec, s[0:1]
	v_cndmask_b32_e64 v180, v124, v128, s[40:41]
	v_cndmask_b32_e64 v181, v124, v128, s[42:43]
	v_cndmask_b32_e64 v182, v125, v129, s[40:41]
	v_cndmask_b32_e64 v183, v125, v129, s[42:43]
	v_cndmask_b32_e64 v184, v126, v130, s[40:41]
	v_cndmask_b32_e64 v185, v126, v130, s[42:43]
	v_cndmask_b32_e64 v186, v127, v131, s[40:41]
	v_cndmask_b32_e64 v187, v127, v131, s[42:43]
	v_mov_b32_e32 v172, v214
	v_mov_b32_e32 v173, v215
	v_mov_b32_e32 v174, v216
	v_mov_b32_e32 v175, v217
	v_fmac_f32_dpp v172, v180, v202 row_ror:2 row_mask:0xf bank_mask:0xf
	v_fmac_f32_dpp v173, v182, v203 row_ror:2 row_mask:0xf bank_mask:0xf
	v_fmac_f32_dpp v174, v184, v204 row_ror:2 row_mask:0xf bank_mask:0xf
	v_fmac_f32_dpp v175, v186, v205 row_ror:2 row_mask:0xf bank_mask:0xf
	v_fmac_f32_dpp v172, v181, v206 row_ror:1 row_mask:0xf bank_mask:0xf
	v_fmac_f32_dpp v173, v183, v207 row_ror:1 row_mask:0xf bank_mask:0xf
	v_fmac_f32_dpp v174, v185, v208 row_ror:1 row_mask:0xf bank_mask:0xf
	v_fmac_f32_dpp v175, v187, v209 row_ror:1 row_mask:0xf bank_mask:0xf
	v_fmac_f32_e32 v172, v124, v210
	v_fmac_f32_e32 v173, v125, v211
	v_fmac_f32_e32 v174, v126, v212
	v_fmac_f32_e32 v175, v127, v213
	v_cndmask_b32_e64 v180, v116, v120, s[40:41]
	v_cndmask_b32_e64 v181, v116, v120, s[42:43]
	v_cndmask_b32_e64 v182, v117, v121, s[40:41]
	v_cndmask_b32_e64 v183, v117, v121, s[42:43]
	v_cndmask_b32_e64 v184, v118, v122, s[40:41]
	v_cndmask_b32_e64 v185, v118, v122, s[42:43]
	v_cndmask_b32_e64 v186, v119, v123, s[40:41]
	v_cndmask_b32_e64 v187, v119, v123, s[42:43]
	v_mov_b32_e32 v176, v230
	v_mov_b32_e32 v177, v231
	v_mov_b32_e32 v178, v232
	v_mov_b32_e32 v179, v233
	v_fmac_f32_dpp v176, v180, v218 row_ror:2 row_mask:0xf bank_mask:0xf
	v_fmac_f32_dpp v177, v182, v219 row_ror:2 row_mask:0xf bank_mask:0xf
	v_fmac_f32_dpp v178, v184, v220 row_ror:2 row_mask:0xf bank_mask:0xf
	v_fmac_f32_dpp v179, v186, v221 row_ror:2 row_mask:0xf bank_mask:0xf
	v_fmac_f32_dpp v176, v181, v222 row_ror:1 row_mask:0xf bank_mask:0xf
	v_fmac_f32_dpp v177, v183, v223 row_ror:1 row_mask:0xf bank_mask:0xf
	v_fmac_f32_dpp v178, v185, v224 row_ror:1 row_mask:0xf bank_mask:0xf
	v_fmac_f32_dpp v179, v187, v225 row_ror:1 row_mask:0xf bank_mask:0xf
	v_fmac_f32_e32 v176, v116, v226
	v_fmac_f32_e32 v177, v117, v227
	v_fmac_f32_e32 v178, v118, v228
	v_fmac_f32_e32 v179, v119, v229
	v_mul_f32_e32 v132, 0xbfb8aa3b, v172
	v_mul_f32_e32 v133, 0xbfb8aa3b, v173
	v_mul_f32_e32 v134, 0xbfb8aa3b, v174
	v_mul_f32_e32 v135, 0xbfb8aa3b, v175
	v_exp_f32_e32 v132, v132
	v_exp_f32_e32 v133, v133
	v_exp_f32_e32 v134, v134
	v_exp_f32_e32 v135, v135
	v_add_f32_e32 v132, 1.0, v132
	v_add_f32_e32 v133, 1.0, v133
	v_add_f32_e32 v134, 1.0, v134
	v_add_f32_e32 v135, 1.0, v135
	v_rcp_f32_e32 v132, v132
	v_rcp_f32_e32 v133, v133
	v_rcp_f32_e32 v134, v134
	v_rcp_f32_e32 v135, v135
	v_mul_f32_e32 v132, v172, v132
	v_mul_f32_e32 v133, v173, v133
	v_mul_f32_e32 v134, v174, v134
	v_mul_f32_e32 v135, v175, v135
	v_mul_f32_e32 v132, v132, v176
	v_mul_f32_e32 v133, v133, v177
	v_mul_f32_e32 v134, v134, v178
	v_mul_f32_e32 v135, v135, v179
	v_cvt_pk_bf16_f32 v138, v132, v133
	v_cvt_pk_bf16_f32 v139, v134, v135
	v_add_u32_e32 v165, 0x30800, v164
	global_store_dwordx2 v165, v[138:139], s[34:35] offset:2048
	v_cndmask_b32_e64 v180, v96, v124, s[40:41]
	v_cndmask_b32_e64 v181, v96, v124, s[42:43]
	v_cndmask_b32_e64 v182, v97, v125, s[40:41]
	v_cndmask_b32_e64 v183, v97, v125, s[42:43]
	v_cndmask_b32_e64 v184, v98, v126, s[40:41]
	v_cndmask_b32_e64 v185, v98, v126, s[42:43]
	v_cndmask_b32_e64 v186, v99, v127, s[40:41]
	v_cndmask_b32_e64 v187, v99, v127, s[42:43]
	v_mov_b32_e32 v172, v214
	v_mov_b32_e32 v173, v215
	v_mov_b32_e32 v174, v216
	v_mov_b32_e32 v175, v217
	v_fmac_f32_dpp v172, v180, v202 row_ror:2 row_mask:0xf bank_mask:0xf
	v_fmac_f32_dpp v173, v182, v203 row_ror:2 row_mask:0xf bank_mask:0xf
	v_fmac_f32_dpp v174, v184, v204 row_ror:2 row_mask:0xf bank_mask:0xf
	v_fmac_f32_dpp v175, v186, v205 row_ror:2 row_mask:0xf bank_mask:0xf
	v_fmac_f32_dpp v172, v181, v206 row_ror:1 row_mask:0xf bank_mask:0xf
	v_fmac_f32_dpp v173, v183, v207 row_ror:1 row_mask:0xf bank_mask:0xf
	v_fmac_f32_dpp v174, v185, v208 row_ror:1 row_mask:0xf bank_mask:0xf
	v_fmac_f32_dpp v175, v187, v209 row_ror:1 row_mask:0xf bank_mask:0xf
	v_fmac_f32_e32 v172, v96, v210
	v_fmac_f32_e32 v173, v97, v211
	v_fmac_f32_e32 v174, v98, v212
	v_fmac_f32_e32 v175, v99, v213
	v_cndmask_b32_e64 v180, v92, v116, s[40:41]
	v_cndmask_b32_e64 v181, v92, v116, s[42:43]
	v_cndmask_b32_e64 v182, v93, v117, s[40:41]
	v_cndmask_b32_e64 v183, v93, v117, s[42:43]
	v_cndmask_b32_e64 v184, v94, v118, s[40:41]
	v_cndmask_b32_e64 v185, v94, v118, s[42:43]
	v_cndmask_b32_e64 v186, v95, v119, s[40:41]
	v_cndmask_b32_e64 v187, v95, v119, s[42:43]
	v_mov_b32_e32 v176, v230
	v_mov_b32_e32 v177, v231
	v_mov_b32_e32 v178, v232
	v_mov_b32_e32 v179, v233
	v_fmac_f32_dpp v176, v180, v218 row_ror:2 row_mask:0xf bank_mask:0xf
	v_fmac_f32_dpp v177, v182, v219 row_ror:2 row_mask:0xf bank_mask:0xf
	v_fmac_f32_dpp v178, v184, v220 row_ror:2 row_mask:0xf bank_mask:0xf
	v_fmac_f32_dpp v179, v186, v221 row_ror:2 row_mask:0xf bank_mask:0xf
	v_fmac_f32_dpp v176, v181, v222 row_ror:1 row_mask:0xf bank_mask:0xf
	v_fmac_f32_dpp v177, v183, v223 row_ror:1 row_mask:0xf bank_mask:0xf
	v_fmac_f32_dpp v178, v185, v224 row_ror:1 row_mask:0xf bank_mask:0xf
	v_fmac_f32_dpp v179, v187, v225 row_ror:1 row_mask:0xf bank_mask:0xf
	v_fmac_f32_e32 v176, v92, v226
	v_fmac_f32_e32 v177, v93, v227
	v_fmac_f32_e32 v178, v94, v228
	v_fmac_f32_e32 v179, v95, v229
	v_mul_f32_e32 v132, 0xbfb8aa3b, v172
	v_mul_f32_e32 v133, 0xbfb8aa3b, v173
	v_mul_f32_e32 v134, 0xbfb8aa3b, v174
	v_mul_f32_e32 v135, 0xbfb8aa3b, v175
	v_exp_f32_e32 v132, v132
	v_exp_f32_e32 v133, v133
	v_exp_f32_e32 v134, v134
	v_exp_f32_e32 v135, v135
	v_add_f32_e32 v132, 1.0, v132
	v_add_f32_e32 v133, 1.0, v133
	v_add_f32_e32 v134, 1.0, v134
	v_add_f32_e32 v135, 1.0, v135
	v_rcp_f32_e32 v132, v132
	v_rcp_f32_e32 v133, v133
	v_rcp_f32_e32 v134, v134
	v_rcp_f32_e32 v135, v135
	v_mul_f32_e32 v132, v172, v132
	v_mul_f32_e32 v133, v173, v133
	v_mul_f32_e32 v134, v174, v134
	v_mul_f32_e32 v135, v175, v135
	v_mul_f32_e32 v132, v132, v176
	v_mul_f32_e32 v133, v133, v177
	v_mul_f32_e32 v134, v134, v178
	v_mul_f32_e32 v135, v135, v179
	v_cvt_pk_bf16_f32 v136, v132, v133
	v_cvt_pk_bf16_f32 v137, v134, v135
	v_add_u32_e32 v165, 0x61000, v164
	global_store_dwordx2 v165, v[136:137], s[34:35] offset:2048
	v_cndmask_b32_e64 v180, v80, v96, s[40:41]
	v_cndmask_b32_e64 v181, v80, v96, s[42:43]
	v_cndmask_b32_e64 v182, v81, v97, s[40:41]
	v_cndmask_b32_e64 v183, v81, v97, s[42:43]
	v_cndmask_b32_e64 v184, v82, v98, s[40:41]
	v_cndmask_b32_e64 v185, v82, v98, s[42:43]
	v_cndmask_b32_e64 v186, v83, v99, s[40:41]
	v_cndmask_b32_e64 v187, v83, v99, s[42:43]
	v_mov_b32_e32 v172, v214
	v_mov_b32_e32 v173, v215
	v_mov_b32_e32 v174, v216
	v_mov_b32_e32 v175, v217
	v_fmac_f32_dpp v172, v180, v202 row_ror:2 row_mask:0xf bank_mask:0xf
	v_fmac_f32_dpp v173, v182, v203 row_ror:2 row_mask:0xf bank_mask:0xf
	v_fmac_f32_dpp v174, v184, v204 row_ror:2 row_mask:0xf bank_mask:0xf
	v_fmac_f32_dpp v175, v186, v205 row_ror:2 row_mask:0xf bank_mask:0xf
	v_fmac_f32_dpp v172, v181, v206 row_ror:1 row_mask:0xf bank_mask:0xf
	v_fmac_f32_dpp v173, v183, v207 row_ror:1 row_mask:0xf bank_mask:0xf
	v_fmac_f32_dpp v174, v185, v208 row_ror:1 row_mask:0xf bank_mask:0xf
	v_fmac_f32_dpp v175, v187, v209 row_ror:1 row_mask:0xf bank_mask:0xf
	v_fmac_f32_e32 v172, v80, v210
	v_fmac_f32_e32 v173, v81, v211
	v_fmac_f32_e32 v174, v82, v212
	v_fmac_f32_e32 v175, v83, v213
	v_cndmask_b32_e64 v180, v76, v92, s[40:41]
	v_cndmask_b32_e64 v181, v76, v92, s[42:43]
	v_cndmask_b32_e64 v182, v77, v93, s[40:41]
	v_cndmask_b32_e64 v183, v77, v93, s[42:43]
	v_cndmask_b32_e64 v184, v78, v94, s[40:41]
	v_cndmask_b32_e64 v185, v78, v94, s[42:43]
	v_cndmask_b32_e64 v186, v79, v95, s[40:41]
	v_cndmask_b32_e64 v187, v79, v95, s[42:43]
	v_mov_b32_e32 v176, v230
	v_mov_b32_e32 v177, v231
	v_mov_b32_e32 v178, v232
	v_mov_b32_e32 v179, v233
	v_fmac_f32_dpp v176, v180, v218 row_ror:2 row_mask:0xf bank_mask:0xf
	v_fmac_f32_dpp v177, v182, v219 row_ror:2 row_mask:0xf bank_mask:0xf
	v_fmac_f32_dpp v178, v184, v220 row_ror:2 row_mask:0xf bank_mask:0xf
	v_fmac_f32_dpp v179, v186, v221 row_ror:2 row_mask:0xf bank_mask:0xf
	v_fmac_f32_dpp v176, v181, v222 row_ror:1 row_mask:0xf bank_mask:0xf
	v_fmac_f32_dpp v177, v183, v223 row_ror:1 row_mask:0xf bank_mask:0xf
	v_fmac_f32_dpp v178, v185, v224 row_ror:1 row_mask:0xf bank_mask:0xf
	v_fmac_f32_dpp v179, v187, v225 row_ror:1 row_mask:0xf bank_mask:0xf
	v_fmac_f32_e32 v176, v76, v226
	v_fmac_f32_e32 v177, v77, v227
	v_fmac_f32_e32 v178, v78, v228
	v_fmac_f32_e32 v179, v79, v229
	v_mul_f32_e32 v132, 0xbfb8aa3b, v172
	v_mul_f32_e32 v133, 0xbfb8aa3b, v173
	v_mul_f32_e32 v134, 0xbfb8aa3b, v174
	v_mul_f32_e32 v135, 0xbfb8aa3b, v175
	v_exp_f32_e32 v132, v132
	v_exp_f32_e32 v133, v133
	v_exp_f32_e32 v134, v134
	v_exp_f32_e32 v135, v135
	v_add_f32_e32 v132, 1.0, v132
	v_add_f32_e32 v133, 1.0, v133
	v_add_f32_e32 v134, 1.0, v134
	v_add_f32_e32 v135, 1.0, v135
	v_rcp_f32_e32 v132, v132
	v_rcp_f32_e32 v133, v133
	v_rcp_f32_e32 v134, v134
	v_rcp_f32_e32 v135, v135
	v_mul_f32_e32 v132, v172, v132
	v_mul_f32_e32 v133, v173, v133
	v_mul_f32_e32 v134, v174, v134
	v_mul_f32_e32 v135, v175, v135
	v_mul_f32_e32 v132, v132, v176
	v_mul_f32_e32 v133, v133, v177
	v_mul_f32_e32 v134, v134, v178
	v_mul_f32_e32 v135, v135, v179
	v_cvt_pk_bf16_f32 v138, v132, v133
	v_cvt_pk_bf16_f32 v139, v134, v135
	v_add_u32_e32 v165, 0x91800, v164
	global_store_dwordx2 v165, v[138:139], s[34:35] offset:2048
	v_cndmask_b32_e64 v180, v64, v31, s[40:41]
	v_cndmask_b32_e64 v181, v64, v31, s[42:43]
	v_cndmask_b32_e64 v182, v65, v31, s[40:41]
	v_cndmask_b32_e64 v183, v65, v31, s[42:43]
	v_cndmask_b32_e64 v184, v66, v31, s[40:41]
	v_cndmask_b32_e64 v185, v66, v31, s[42:43]
	v_cndmask_b32_e64 v186, v67, v31, s[40:41]
	v_cndmask_b32_e64 v187, v67, v31, s[42:43]
	v_mov_b32_e32 v172, v214
	v_mov_b32_e32 v173, v215
	v_mov_b32_e32 v174, v216
	v_mov_b32_e32 v175, v217
	v_fmac_f32_dpp v172, v180, v202 row_ror:2 row_mask:0xf bank_mask:0xf
	v_fmac_f32_dpp v173, v182, v203 row_ror:2 row_mask:0xf bank_mask:0xf
	v_fmac_f32_dpp v174, v184, v204 row_ror:2 row_mask:0xf bank_mask:0xf
	v_fmac_f32_dpp v175, v186, v205 row_ror:2 row_mask:0xf bank_mask:0xf
	v_fmac_f32_dpp v172, v181, v206 row_ror:1 row_mask:0xf bank_mask:0xf
	v_fmac_f32_dpp v173, v183, v207 row_ror:1 row_mask:0xf bank_mask:0xf
	v_fmac_f32_dpp v174, v185, v208 row_ror:1 row_mask:0xf bank_mask:0xf
	v_fmac_f32_dpp v175, v187, v209 row_ror:1 row_mask:0xf bank_mask:0xf
	v_fmac_f32_e32 v172, v64, v210
	v_fmac_f32_e32 v173, v65, v211
	v_fmac_f32_e32 v174, v66, v212
	v_fmac_f32_e32 v175, v67, v213
	v_cndmask_b32_e64 v180, v56, v31, s[40:41]
	v_cndmask_b32_e64 v181, v56, v31, s[42:43]
	v_cndmask_b32_e64 v182, v57, v31, s[40:41]
	v_cndmask_b32_e64 v183, v57, v31, s[42:43]
	v_cndmask_b32_e64 v184, v58, v31, s[40:41]
	v_cndmask_b32_e64 v185, v58, v31, s[42:43]
	v_cndmask_b32_e64 v186, v59, v31, s[40:41]
	v_cndmask_b32_e64 v187, v59, v31, s[42:43]
	v_mov_b32_e32 v176, v230
	v_mov_b32_e32 v177, v231
	v_mov_b32_e32 v178, v232
	v_mov_b32_e32 v179, v233
	v_fmac_f32_dpp v176, v180, v218 row_ror:2 row_mask:0xf bank_mask:0xf
	v_fmac_f32_dpp v177, v182, v219 row_ror:2 row_mask:0xf bank_mask:0xf
	v_fmac_f32_dpp v178, v184, v220 row_ror:2 row_mask:0xf bank_mask:0xf
	v_fmac_f32_dpp v179, v186, v221 row_ror:2 row_mask:0xf bank_mask:0xf
	v_fmac_f32_dpp v176, v181, v222 row_ror:1 row_mask:0xf bank_mask:0xf
	v_fmac_f32_dpp v177, v183, v223 row_ror:1 row_mask:0xf bank_mask:0xf
	v_fmac_f32_dpp v178, v185, v224 row_ror:1 row_mask:0xf bank_mask:0xf
	v_fmac_f32_dpp v179, v187, v225 row_ror:1 row_mask:0xf bank_mask:0xf
	v_fmac_f32_e32 v176, v56, v226
	v_fmac_f32_e32 v177, v57, v227
	v_fmac_f32_e32 v178, v58, v228
	v_fmac_f32_e32 v179, v59, v229
	v_mul_f32_e32 v132, 0xbfb8aa3b, v172
	v_mul_f32_e32 v133, 0xbfb8aa3b, v173
	v_mul_f32_e32 v134, 0xbfb8aa3b, v174
	v_mul_f32_e32 v135, 0xbfb8aa3b, v175
	v_exp_f32_e32 v132, v132
	v_exp_f32_e32 v133, v133
	v_exp_f32_e32 v134, v134
	v_exp_f32_e32 v135, v135
	v_add_f32_e32 v132, 1.0, v132
	v_add_f32_e32 v133, 1.0, v133
	v_add_f32_e32 v134, 1.0, v134
	v_add_f32_e32 v135, 1.0, v135
	v_rcp_f32_e32 v132, v132
	v_rcp_f32_e32 v133, v133
	v_rcp_f32_e32 v134, v134
	v_rcp_f32_e32 v135, v135
	v_mul_f32_e32 v132, v172, v132
	v_mul_f32_e32 v133, v173, v133
	v_mul_f32_e32 v134, v174, v134
	v_mul_f32_e32 v135, v175, v135
	v_mul_f32_e32 v132, v132, v176
	v_mul_f32_e32 v133, v133, v177
	v_mul_f32_e32 v134, v134, v178
	v_mul_f32_e32 v135, v135, v179
	v_cvt_pk_bf16_f32 v136, v132, v133
	v_cvt_pk_bf16_f32 v137, v134, v135
	v_add_u32_e32 v165, 0x184000, v164
	s_and_saveexec_b64 s[0:1], s[44:45]
	global_store_dwordx2 v165, v[136:137], s[34:35] offset:2048
	s_or_b64 exec, exec, s[0:1]
	v_cndmask_b32_e64 v180, v60, v64, s[40:41]
	v_cndmask_b32_e64 v181, v60, v64, s[42:43]
	v_cndmask_b32_e64 v182, v61, v65, s[40:41]
	v_cndmask_b32_e64 v183, v61, v65, s[42:43]
	v_cndmask_b32_e64 v184, v62, v66, s[40:41]
	v_cndmask_b32_e64 v185, v62, v66, s[42:43]
	v_cndmask_b32_e64 v186, v63, v67, s[40:41]
	v_cndmask_b32_e64 v187, v63, v67, s[42:43]
	v_mov_b32_e32 v172, v214
	v_mov_b32_e32 v173, v215
	v_mov_b32_e32 v174, v216
	v_mov_b32_e32 v175, v217
	v_fmac_f32_dpp v172, v180, v202 row_ror:2 row_mask:0xf bank_mask:0xf
	v_fmac_f32_dpp v173, v182, v203 row_ror:2 row_mask:0xf bank_mask:0xf
	v_fmac_f32_dpp v174, v184, v204 row_ror:2 row_mask:0xf bank_mask:0xf
	v_fmac_f32_dpp v175, v186, v205 row_ror:2 row_mask:0xf bank_mask:0xf
	v_fmac_f32_dpp v172, v181, v206 row_ror:1 row_mask:0xf bank_mask:0xf
	v_fmac_f32_dpp v173, v183, v207 row_ror:1 row_mask:0xf bank_mask:0xf
	v_fmac_f32_dpp v174, v185, v208 row_ror:1 row_mask:0xf bank_mask:0xf
	v_fmac_f32_dpp v175, v187, v209 row_ror:1 row_mask:0xf bank_mask:0xf
	v_fmac_f32_e32 v172, v60, v210
	v_fmac_f32_e32 v173, v61, v211
	v_fmac_f32_e32 v174, v62, v212
	v_fmac_f32_e32 v175, v63, v213
	v_cndmask_b32_e64 v180, v52, v56, s[40:41]
	v_cndmask_b32_e64 v181, v52, v56, s[42:43]
	v_cndmask_b32_e64 v182, v53, v57, s[40:41]
	v_cndmask_b32_e64 v183, v53, v57, s[42:43]
	v_cndmask_b32_e64 v184, v54, v58, s[40:41]
	v_cndmask_b32_e64 v185, v54, v58, s[42:43]
	v_cndmask_b32_e64 v186, v55, v59, s[40:41]
	v_cndmask_b32_e64 v187, v55, v59, s[42:43]
	v_mov_b32_e32 v176, v230
	v_mov_b32_e32 v177, v231
	v_mov_b32_e32 v178, v232
	v_mov_b32_e32 v179, v233
	v_fmac_f32_dpp v176, v180, v218 row_ror:2 row_mask:0xf bank_mask:0xf
	v_fmac_f32_dpp v177, v182, v219 row_ror:2 row_mask:0xf bank_mask:0xf
	v_fmac_f32_dpp v178, v184, v220 row_ror:2 row_mask:0xf bank_mask:0xf
	v_fmac_f32_dpp v179, v186, v221 row_ror:2 row_mask:0xf bank_mask:0xf
	v_fmac_f32_dpp v176, v181, v222 row_ror:1 row_mask:0xf bank_mask:0xf
	v_fmac_f32_dpp v177, v183, v223 row_ror:1 row_mask:0xf bank_mask:0xf
	v_fmac_f32_dpp v178, v185, v224 row_ror:1 row_mask:0xf bank_mask:0xf
	v_fmac_f32_dpp v179, v187, v225 row_ror:1 row_mask:0xf bank_mask:0xf
	v_fmac_f32_e32 v176, v52, v226
	v_fmac_f32_e32 v177, v53, v227
	v_fmac_f32_e32 v178, v54, v228
	v_fmac_f32_e32 v179, v55, v229
	v_mul_f32_e32 v132, 0xbfb8aa3b, v172
	v_mul_f32_e32 v133, 0xbfb8aa3b, v173
	v_mul_f32_e32 v134, 0xbfb8aa3b, v174
	v_mul_f32_e32 v135, 0xbfb8aa3b, v175
	v_exp_f32_e32 v132, v132
	v_exp_f32_e32 v133, v133
	v_exp_f32_e32 v134, v134
	v_exp_f32_e32 v135, v135
	v_add_f32_e32 v132, 1.0, v132
	v_add_f32_e32 v133, 1.0, v133
	v_add_f32_e32 v134, 1.0, v134
	v_add_f32_e32 v135, 1.0, v135
	v_rcp_f32_e32 v132, v132
	v_rcp_f32_e32 v133, v133
	v_rcp_f32_e32 v134, v134
	v_rcp_f32_e32 v135, v135
	v_mul_f32_e32 v132, v172, v132
	v_mul_f32_e32 v133, v173, v133
	v_mul_f32_e32 v134, v174, v134
	v_mul_f32_e32 v135, v175, v135
	v_mul_f32_e32 v132, v132, v176
	v_mul_f32_e32 v133, v133, v177
	v_mul_f32_e32 v134, v134, v178
	v_mul_f32_e32 v135, v135, v179
	v_cvt_pk_bf16_f32 v138, v132, v133
	v_cvt_pk_bf16_f32 v139, v134, v135
	v_add_u32_e32 v165, 0x1b4800, v164
	global_store_dwordx2 v165, v[138:139], s[34:35] offset:2048
	v_cndmask_b32_e64 v180, v32, v60, s[40:41]
	v_cndmask_b32_e64 v181, v32, v60, s[42:43]
	v_cndmask_b32_e64 v182, v33, v61, s[40:41]
	v_cndmask_b32_e64 v183, v33, v61, s[42:43]
	v_cndmask_b32_e64 v184, v34, v62, s[40:41]
	v_cndmask_b32_e64 v185, v34, v62, s[42:43]
	v_cndmask_b32_e64 v186, v35, v63, s[40:41]
	v_cndmask_b32_e64 v187, v35, v63, s[42:43]
	v_mov_b32_e32 v172, v214
	v_mov_b32_e32 v173, v215
	v_mov_b32_e32 v174, v216
	v_mov_b32_e32 v175, v217
	v_fmac_f32_dpp v172, v180, v202 row_ror:2 row_mask:0xf bank_mask:0xf
	v_fmac_f32_dpp v173, v182, v203 row_ror:2 row_mask:0xf bank_mask:0xf
	v_fmac_f32_dpp v174, v184, v204 row_ror:2 row_mask:0xf bank_mask:0xf
	v_fmac_f32_dpp v175, v186, v205 row_ror:2 row_mask:0xf bank_mask:0xf
	v_fmac_f32_dpp v172, v181, v206 row_ror:1 row_mask:0xf bank_mask:0xf
	v_fmac_f32_dpp v173, v183, v207 row_ror:1 row_mask:0xf bank_mask:0xf
	v_fmac_f32_dpp v174, v185, v208 row_ror:1 row_mask:0xf bank_mask:0xf
	v_fmac_f32_dpp v175, v187, v209 row_ror:1 row_mask:0xf bank_mask:0xf
	v_fmac_f32_e32 v172, v32, v210
	v_fmac_f32_e32 v173, v33, v211
	v_fmac_f32_e32 v174, v34, v212
	v_fmac_f32_e32 v175, v35, v213
	v_cndmask_b32_e64 v180, v24, v52, s[40:41]
	v_cndmask_b32_e64 v181, v24, v52, s[42:43]
	v_cndmask_b32_e64 v182, v25, v53, s[40:41]
	v_cndmask_b32_e64 v183, v25, v53, s[42:43]
	v_cndmask_b32_e64 v184, v26, v54, s[40:41]
	v_cndmask_b32_e64 v185, v26, v54, s[42:43]
	v_cndmask_b32_e64 v186, v27, v55, s[40:41]
	v_cndmask_b32_e64 v187, v27, v55, s[42:43]
	v_mov_b32_e32 v176, v230
	v_mov_b32_e32 v177, v231
	v_mov_b32_e32 v178, v232
	v_mov_b32_e32 v179, v233
	v_fmac_f32_dpp v176, v180, v218 row_ror:2 row_mask:0xf bank_mask:0xf
	v_fmac_f32_dpp v177, v182, v219 row_ror:2 row_mask:0xf bank_mask:0xf
	v_fmac_f32_dpp v178, v184, v220 row_ror:2 row_mask:0xf bank_mask:0xf
	v_fmac_f32_dpp v179, v186, v221 row_ror:2 row_mask:0xf bank_mask:0xf
	v_fmac_f32_dpp v176, v181, v222 row_ror:1 row_mask:0xf bank_mask:0xf
	v_fmac_f32_dpp v177, v183, v223 row_ror:1 row_mask:0xf bank_mask:0xf
	v_fmac_f32_dpp v178, v185, v224 row_ror:1 row_mask:0xf bank_mask:0xf
	v_fmac_f32_dpp v179, v187, v225 row_ror:1 row_mask:0xf bank_mask:0xf
	v_fmac_f32_e32 v176, v24, v226
	v_fmac_f32_e32 v177, v25, v227
	v_fmac_f32_e32 v178, v26, v228
	v_fmac_f32_e32 v179, v27, v229
	v_mul_f32_e32 v132, 0xbfb8aa3b, v172
	v_mul_f32_e32 v133, 0xbfb8aa3b, v173
	v_mul_f32_e32 v134, 0xbfb8aa3b, v174
	v_mul_f32_e32 v135, 0xbfb8aa3b, v175
	v_exp_f32_e32 v132, v132
	v_exp_f32_e32 v133, v133
	v_exp_f32_e32 v134, v134
	v_exp_f32_e32 v135, v135
	v_add_f32_e32 v132, 1.0, v132
	v_add_f32_e32 v133, 1.0, v133
	v_add_f32_e32 v134, 1.0, v134
	v_add_f32_e32 v135, 1.0, v135
	v_rcp_f32_e32 v132, v132
	v_rcp_f32_e32 v133, v133
	v_rcp_f32_e32 v134, v134
	v_rcp_f32_e32 v135, v135
	v_mul_f32_e32 v132, v172, v132
	v_mul_f32_e32 v133, v173, v133
	v_mul_f32_e32 v134, v174, v134
	v_mul_f32_e32 v135, v175, v135
	v_mul_f32_e32 v132, v132, v176
	v_mul_f32_e32 v133, v133, v177
	v_mul_f32_e32 v134, v134, v178
	v_mul_f32_e32 v135, v135, v179
	v_cvt_pk_bf16_f32 v136, v132, v133
	v_cvt_pk_bf16_f32 v137, v134, v135
	v_add_u32_e32 v165, 0x1e5000, v164
	global_store_dwordx2 v165, v[136:137], s[34:35] offset:2048
	v_cndmask_b32_e64 v180, v12, v32, s[40:41]
	v_cndmask_b32_e64 v181, v12, v32, s[42:43]
	v_cndmask_b32_e64 v182, v13, v33, s[40:41]
	v_cndmask_b32_e64 v183, v13, v33, s[42:43]
	v_cndmask_b32_e64 v184, v14, v34, s[40:41]
	v_cndmask_b32_e64 v185, v14, v34, s[42:43]
	v_cndmask_b32_e64 v186, v15, v35, s[40:41]
	v_cndmask_b32_e64 v187, v15, v35, s[42:43]
	v_mov_b32_e32 v172, v214
	v_mov_b32_e32 v173, v215
	v_mov_b32_e32 v174, v216
	v_mov_b32_e32 v175, v217
	v_fmac_f32_dpp v172, v180, v202 row_ror:2 row_mask:0xf bank_mask:0xf
	v_fmac_f32_dpp v173, v182, v203 row_ror:2 row_mask:0xf bank_mask:0xf
	v_fmac_f32_dpp v174, v184, v204 row_ror:2 row_mask:0xf bank_mask:0xf
	v_fmac_f32_dpp v175, v186, v205 row_ror:2 row_mask:0xf bank_mask:0xf
	v_fmac_f32_dpp v172, v181, v206 row_ror:1 row_mask:0xf bank_mask:0xf
	v_fmac_f32_dpp v173, v183, v207 row_ror:1 row_mask:0xf bank_mask:0xf
	v_fmac_f32_dpp v174, v185, v208 row_ror:1 row_mask:0xf bank_mask:0xf
	v_fmac_f32_dpp v175, v187, v209 row_ror:1 row_mask:0xf bank_mask:0xf
	v_fmac_f32_e32 v172, v12, v210
	v_fmac_f32_e32 v173, v13, v211
	v_fmac_f32_e32 v174, v14, v212
	v_fmac_f32_e32 v175, v15, v213
	v_cndmask_b32_e64 v180, v8, v24, s[40:41]
	v_cndmask_b32_e64 v181, v8, v24, s[42:43]
	v_cndmask_b32_e64 v182, v9, v25, s[40:41]
	v_cndmask_b32_e64 v183, v9, v25, s[42:43]
	v_cndmask_b32_e64 v184, v10, v26, s[40:41]
	v_cndmask_b32_e64 v185, v10, v26, s[42:43]
	v_cndmask_b32_e64 v186, v11, v27, s[40:41]
	v_cndmask_b32_e64 v187, v11, v27, s[42:43]
	v_mov_b32_e32 v176, v230
	v_mov_b32_e32 v177, v231
	v_mov_b32_e32 v178, v232
	v_mov_b32_e32 v179, v233
	v_fmac_f32_dpp v176, v180, v218 row_ror:2 row_mask:0xf bank_mask:0xf
	v_fmac_f32_dpp v177, v182, v219 row_ror:2 row_mask:0xf bank_mask:0xf
	v_fmac_f32_dpp v178, v184, v220 row_ror:2 row_mask:0xf bank_mask:0xf
	v_fmac_f32_dpp v179, v186, v221 row_ror:2 row_mask:0xf bank_mask:0xf
	v_fmac_f32_dpp v176, v181, v222 row_ror:1 row_mask:0xf bank_mask:0xf
	v_fmac_f32_dpp v177, v183, v223 row_ror:1 row_mask:0xf bank_mask:0xf
	v_fmac_f32_dpp v178, v185, v224 row_ror:1 row_mask:0xf bank_mask:0xf
	v_fmac_f32_dpp v179, v187, v225 row_ror:1 row_mask:0xf bank_mask:0xf
	v_fmac_f32_e32 v176, v8, v226
	v_fmac_f32_e32 v177, v9, v227
	v_fmac_f32_e32 v178, v10, v228
	v_fmac_f32_e32 v179, v11, v229
	v_mul_f32_e32 v132, 0xbfb8aa3b, v172
	v_mul_f32_e32 v133, 0xbfb8aa3b, v173
	v_mul_f32_e32 v134, 0xbfb8aa3b, v174
	v_mul_f32_e32 v135, 0xbfb8aa3b, v175
	v_exp_f32_e32 v132, v132
	v_exp_f32_e32 v133, v133
	v_exp_f32_e32 v134, v134
	v_exp_f32_e32 v135, v135
	v_add_f32_e32 v132, 1.0, v132
	v_add_f32_e32 v133, 1.0, v133
	v_add_f32_e32 v134, 1.0, v134
	v_add_f32_e32 v135, 1.0, v135
	v_rcp_f32_e32 v132, v132
	v_rcp_f32_e32 v133, v133
	v_rcp_f32_e32 v134, v134
	v_rcp_f32_e32 v135, v135
	v_mul_f32_e32 v132, v172, v132
	v_mul_f32_e32 v133, v173, v133
	v_mul_f32_e32 v134, v174, v134
	v_mul_f32_e32 v135, v175, v135
	v_mul_f32_e32 v132, v132, v176
	v_mul_f32_e32 v133, v133, v177
	v_mul_f32_e32 v134, v134, v178
	v_mul_f32_e32 v135, v135, v179
	v_cvt_pk_bf16_f32 v138, v132, v133
	v_cvt_pk_bf16_f32 v139, v134, v135
	v_add_u32_e32 v165, 0x215800, v164
	global_store_dwordx2 v165, v[138:139], s[34:35] offset:2048
	ds_read_b128 v[202:205], v166 offset:16
	ds_read_b128 v[206:209], v166 offset:1040
	ds_read_b128 v[210:213], v166 offset:2064
	ds_read_b128 v[214:217], v166 offset:3088
	ds_read_b128 v[218:221], v166 offset:528
	ds_read_b128 v[222:225], v166 offset:1552
	ds_read_b128 v[226:229], v166 offset:2576
	ds_read_b128 v[230:233], v166 offset:3600
	s_waitcnt lgkmcnt(0)
	v_cndmask_b32_e64 v180, v112, v31, s[40:41]
	v_cndmask_b32_e64 v181, v112, v31, s[42:43]
	v_cndmask_b32_e64 v182, v113, v31, s[40:41]
	v_cndmask_b32_e64 v183, v113, v31, s[42:43]
	v_cndmask_b32_e64 v184, v114, v31, s[40:41]
	v_cndmask_b32_e64 v185, v114, v31, s[42:43]
	v_cndmask_b32_e64 v186, v115, v31, s[40:41]
	v_cndmask_b32_e64 v187, v115, v31, s[42:43]
	v_mov_b32_e32 v172, v214
	v_mov_b32_e32 v173, v215
	v_mov_b32_e32 v174, v216
	v_mov_b32_e32 v175, v217
	v_fmac_f32_dpp v172, v180, v202 row_ror:2 row_mask:0xf bank_mask:0xf
	v_fmac_f32_dpp v173, v182, v203 row_ror:2 row_mask:0xf bank_mask:0xf
	v_fmac_f32_dpp v174, v184, v204 row_ror:2 row_mask:0xf bank_mask:0xf
	v_fmac_f32_dpp v175, v186, v205 row_ror:2 row_mask:0xf bank_mask:0xf
	v_fmac_f32_dpp v172, v181, v206 row_ror:1 row_mask:0xf bank_mask:0xf
	v_fmac_f32_dpp v173, v183, v207 row_ror:1 row_mask:0xf bank_mask:0xf
	v_fmac_f32_dpp v174, v185, v208 row_ror:1 row_mask:0xf bank_mask:0xf
	v_fmac_f32_dpp v175, v187, v209 row_ror:1 row_mask:0xf bank_mask:0xf
	v_fmac_f32_e32 v172, v112, v210
	v_fmac_f32_e32 v173, v113, v211
	v_fmac_f32_e32 v174, v114, v212
	v_fmac_f32_e32 v175, v115, v213
	v_cndmask_b32_e64 v180, v104, v31, s[40:41]
	v_cndmask_b32_e64 v181, v104, v31, s[42:43]
	v_cndmask_b32_e64 v182, v105, v31, s[40:41]
	v_cndmask_b32_e64 v183, v105, v31, s[42:43]
	v_cndmask_b32_e64 v184, v106, v31, s[40:41]
	v_cndmask_b32_e64 v185, v106, v31, s[42:43]
	v_cndmask_b32_e64 v186, v107, v31, s[40:41]
	v_cndmask_b32_e64 v187, v107, v31, s[42:43]
	v_mov_b32_e32 v176, v230
	v_mov_b32_e32 v177, v231
	v_mov_b32_e32 v178, v232
	v_mov_b32_e32 v179, v233
	v_fmac_f32_dpp v176, v180, v218 row_ror:2 row_mask:0xf bank_mask:0xf
	v_fmac_f32_dpp v177, v182, v219 row_ror:2 row_mask:0xf bank_mask:0xf
	v_fmac_f32_dpp v178, v184, v220 row_ror:2 row_mask:0xf bank_mask:0xf
	v_fmac_f32_dpp v179, v186, v221 row_ror:2 row_mask:0xf bank_mask:0xf
	v_fmac_f32_dpp v176, v181, v222 row_ror:1 row_mask:0xf bank_mask:0xf
	v_fmac_f32_dpp v177, v183, v223 row_ror:1 row_mask:0xf bank_mask:0xf
	v_fmac_f32_dpp v178, v185, v224 row_ror:1 row_mask:0xf bank_mask:0xf
	v_fmac_f32_dpp v179, v187, v225 row_ror:1 row_mask:0xf bank_mask:0xf
	v_fmac_f32_e32 v176, v104, v226
	v_fmac_f32_e32 v177, v105, v227
	v_fmac_f32_e32 v178, v106, v228
	v_fmac_f32_e32 v179, v107, v229
	v_mul_f32_e32 v132, 0xbfb8aa3b, v172
	v_mul_f32_e32 v133, 0xbfb8aa3b, v173
	v_mul_f32_e32 v134, 0xbfb8aa3b, v174
	v_mul_f32_e32 v135, 0xbfb8aa3b, v175
	v_exp_f32_e32 v132, v132
	v_exp_f32_e32 v133, v133
	v_exp_f32_e32 v134, v134
	v_exp_f32_e32 v135, v135
	v_add_f32_e32 v132, 1.0, v132
	v_add_f32_e32 v133, 1.0, v133
	v_add_f32_e32 v134, 1.0, v134
	v_add_f32_e32 v135, 1.0, v135
	v_rcp_f32_e32 v132, v132
	v_rcp_f32_e32 v133, v133
	v_rcp_f32_e32 v134, v134
	v_rcp_f32_e32 v135, v135
	v_mul_f32_e32 v132, v172, v132
	v_mul_f32_e32 v133, v173, v133
	v_mul_f32_e32 v134, v174, v134
	v_mul_f32_e32 v135, v175, v135
	v_mul_f32_e32 v132, v132, v176
	v_mul_f32_e32 v133, v133, v177
	v_mul_f32_e32 v134, v134, v178
	v_mul_f32_e32 v135, v135, v179
	v_cvt_pk_bf16_f32 v136, v132, v133
	v_cvt_pk_bf16_f32 v137, v134, v135
	v_mov_b32_e32 v165, v164
	s_and_saveexec_b64 s[0:1], s[44:45]
	global_store_dwordx2 v165, v[136:137], s[34:35] offset:2056
	s_or_b64 exec, exec, s[0:1]
	v_cndmask_b32_e64 v180, v108, v112, s[40:41]
	v_cndmask_b32_e64 v181, v108, v112, s[42:43]
	v_cndmask_b32_e64 v182, v109, v113, s[40:41]
	v_cndmask_b32_e64 v183, v109, v113, s[42:43]
	v_cndmask_b32_e64 v184, v110, v114, s[40:41]
	v_cndmask_b32_e64 v185, v110, v114, s[42:43]
	v_cndmask_b32_e64 v186, v111, v115, s[40:41]
	v_cndmask_b32_e64 v187, v111, v115, s[42:43]
	v_mov_b32_e32 v172, v214
	v_mov_b32_e32 v173, v215
	v_mov_b32_e32 v174, v216
	v_mov_b32_e32 v175, v217
	v_fmac_f32_dpp v172, v180, v202 row_ror:2 row_mask:0xf bank_mask:0xf
	v_fmac_f32_dpp v173, v182, v203 row_ror:2 row_mask:0xf bank_mask:0xf
	v_fmac_f32_dpp v174, v184, v204 row_ror:2 row_mask:0xf bank_mask:0xf
	v_fmac_f32_dpp v175, v186, v205 row_ror:2 row_mask:0xf bank_mask:0xf
	v_fmac_f32_dpp v172, v181, v206 row_ror:1 row_mask:0xf bank_mask:0xf
	v_fmac_f32_dpp v173, v183, v207 row_ror:1 row_mask:0xf bank_mask:0xf
	v_fmac_f32_dpp v174, v185, v208 row_ror:1 row_mask:0xf bank_mask:0xf
	v_fmac_f32_dpp v175, v187, v209 row_ror:1 row_mask:0xf bank_mask:0xf
	v_fmac_f32_e32 v172, v108, v210
	v_fmac_f32_e32 v173, v109, v211
	v_fmac_f32_e32 v174, v110, v212
	v_fmac_f32_e32 v175, v111, v213
	v_cndmask_b32_e64 v180, v100, v104, s[40:41]
	v_cndmask_b32_e64 v181, v100, v104, s[42:43]
	v_cndmask_b32_e64 v182, v101, v105, s[40:41]
	v_cndmask_b32_e64 v183, v101, v105, s[42:43]
	v_cndmask_b32_e64 v184, v102, v106, s[40:41]
	v_cndmask_b32_e64 v185, v102, v106, s[42:43]
	v_cndmask_b32_e64 v186, v103, v107, s[40:41]
	v_cndmask_b32_e64 v187, v103, v107, s[42:43]
	v_mov_b32_e32 v176, v230
	v_mov_b32_e32 v177, v231
	v_mov_b32_e32 v178, v232
	v_mov_b32_e32 v179, v233
	v_fmac_f32_dpp v176, v180, v218 row_ror:2 row_mask:0xf bank_mask:0xf
	v_fmac_f32_dpp v177, v182, v219 row_ror:2 row_mask:0xf bank_mask:0xf
	v_fmac_f32_dpp v178, v184, v220 row_ror:2 row_mask:0xf bank_mask:0xf
	v_fmac_f32_dpp v179, v186, v221 row_ror:2 row_mask:0xf bank_mask:0xf
	v_fmac_f32_dpp v176, v181, v222 row_ror:1 row_mask:0xf bank_mask:0xf
	v_fmac_f32_dpp v177, v183, v223 row_ror:1 row_mask:0xf bank_mask:0xf
	v_fmac_f32_dpp v178, v185, v224 row_ror:1 row_mask:0xf bank_mask:0xf
	v_fmac_f32_dpp v179, v187, v225 row_ror:1 row_mask:0xf bank_mask:0xf
	v_fmac_f32_e32 v176, v100, v226
	v_fmac_f32_e32 v177, v101, v227
	v_fmac_f32_e32 v178, v102, v228
	v_fmac_f32_e32 v179, v103, v229
	v_mul_f32_e32 v132, 0xbfb8aa3b, v172
	v_mul_f32_e32 v133, 0xbfb8aa3b, v173
	v_mul_f32_e32 v134, 0xbfb8aa3b, v174
	v_mul_f32_e32 v135, 0xbfb8aa3b, v175
	v_exp_f32_e32 v132, v132
	v_exp_f32_e32 v133, v133
	v_exp_f32_e32 v134, v134
	v_exp_f32_e32 v135, v135
	v_add_f32_e32 v132, 1.0, v132
	v_add_f32_e32 v133, 1.0, v133
	v_add_f32_e32 v134, 1.0, v134
	v_add_f32_e32 v135, 1.0, v135
	v_rcp_f32_e32 v132, v132
	v_rcp_f32_e32 v133, v133
	v_rcp_f32_e32 v134, v134
	v_rcp_f32_e32 v135, v135
	v_mul_f32_e32 v132, v172, v132
	v_mul_f32_e32 v133, v173, v133
	v_mul_f32_e32 v134, v174, v134
	v_mul_f32_e32 v135, v175, v135
	v_mul_f32_e32 v132, v132, v176
	v_mul_f32_e32 v133, v133, v177
	v_mul_f32_e32 v134, v134, v178
	v_mul_f32_e32 v135, v135, v179
	v_cvt_pk_bf16_f32 v138, v132, v133
	v_cvt_pk_bf16_f32 v139, v134, v135
	v_add_u32_e32 v165, 0x30800, v164
	global_store_dwordx2 v165, v[138:139], s[34:35] offset:2056
	v_cndmask_b32_e64 v180, v88, v108, s[40:41]
	v_cndmask_b32_e64 v181, v88, v108, s[42:43]
	v_cndmask_b32_e64 v182, v89, v109, s[40:41]
	v_cndmask_b32_e64 v183, v89, v109, s[42:43]
	v_cndmask_b32_e64 v184, v90, v110, s[40:41]
	v_cndmask_b32_e64 v185, v90, v110, s[42:43]
	v_cndmask_b32_e64 v186, v91, v111, s[40:41]
	v_cndmask_b32_e64 v187, v91, v111, s[42:43]
	v_mov_b32_e32 v172, v214
	v_mov_b32_e32 v173, v215
	v_mov_b32_e32 v174, v216
	v_mov_b32_e32 v175, v217
	v_fmac_f32_dpp v172, v180, v202 row_ror:2 row_mask:0xf bank_mask:0xf
	v_fmac_f32_dpp v173, v182, v203 row_ror:2 row_mask:0xf bank_mask:0xf
	v_fmac_f32_dpp v174, v184, v204 row_ror:2 row_mask:0xf bank_mask:0xf
	v_fmac_f32_dpp v175, v186, v205 row_ror:2 row_mask:0xf bank_mask:0xf
	v_fmac_f32_dpp v172, v181, v206 row_ror:1 row_mask:0xf bank_mask:0xf
	v_fmac_f32_dpp v173, v183, v207 row_ror:1 row_mask:0xf bank_mask:0xf
	v_fmac_f32_dpp v174, v185, v208 row_ror:1 row_mask:0xf bank_mask:0xf
	v_fmac_f32_dpp v175, v187, v209 row_ror:1 row_mask:0xf bank_mask:0xf
	v_fmac_f32_e32 v172, v88, v210
	v_fmac_f32_e32 v173, v89, v211
	v_fmac_f32_e32 v174, v90, v212
	v_fmac_f32_e32 v175, v91, v213
	v_cndmask_b32_e64 v180, v84, v100, s[40:41]
	v_cndmask_b32_e64 v181, v84, v100, s[42:43]
	v_cndmask_b32_e64 v182, v85, v101, s[40:41]
	v_cndmask_b32_e64 v183, v85, v101, s[42:43]
	v_cndmask_b32_e64 v184, v86, v102, s[40:41]
	v_cndmask_b32_e64 v185, v86, v102, s[42:43]
	v_cndmask_b32_e64 v186, v87, v103, s[40:41]
	v_cndmask_b32_e64 v187, v87, v103, s[42:43]
	v_mov_b32_e32 v176, v230
	v_mov_b32_e32 v177, v231
	v_mov_b32_e32 v178, v232
	v_mov_b32_e32 v179, v233
	v_fmac_f32_dpp v176, v180, v218 row_ror:2 row_mask:0xf bank_mask:0xf
	v_fmac_f32_dpp v177, v182, v219 row_ror:2 row_mask:0xf bank_mask:0xf
	v_fmac_f32_dpp v178, v184, v220 row_ror:2 row_mask:0xf bank_mask:0xf
	v_fmac_f32_dpp v179, v186, v221 row_ror:2 row_mask:0xf bank_mask:0xf
	v_fmac_f32_dpp v176, v181, v222 row_ror:1 row_mask:0xf bank_mask:0xf
	v_fmac_f32_dpp v177, v183, v223 row_ror:1 row_mask:0xf bank_mask:0xf
	v_fmac_f32_dpp v178, v185, v224 row_ror:1 row_mask:0xf bank_mask:0xf
	v_fmac_f32_dpp v179, v187, v225 row_ror:1 row_mask:0xf bank_mask:0xf
	v_fmac_f32_e32 v176, v84, v226
	v_fmac_f32_e32 v177, v85, v227
	v_fmac_f32_e32 v178, v86, v228
	v_fmac_f32_e32 v179, v87, v229
	v_mul_f32_e32 v132, 0xbfb8aa3b, v172
	v_mul_f32_e32 v133, 0xbfb8aa3b, v173
	v_mul_f32_e32 v134, 0xbfb8aa3b, v174
	v_mul_f32_e32 v135, 0xbfb8aa3b, v175
	v_exp_f32_e32 v132, v132
	v_exp_f32_e32 v133, v133
	v_exp_f32_e32 v134, v134
	v_exp_f32_e32 v135, v135
	v_add_f32_e32 v132, 1.0, v132
	v_add_f32_e32 v133, 1.0, v133
	v_add_f32_e32 v134, 1.0, v134
	v_add_f32_e32 v135, 1.0, v135
	v_rcp_f32_e32 v132, v132
	v_rcp_f32_e32 v133, v133
	v_rcp_f32_e32 v134, v134
	v_rcp_f32_e32 v135, v135
	v_mul_f32_e32 v132, v172, v132
	v_mul_f32_e32 v133, v173, v133
	v_mul_f32_e32 v134, v174, v134
	v_mul_f32_e32 v135, v175, v135
	v_mul_f32_e32 v132, v132, v176
	v_mul_f32_e32 v133, v133, v177
	v_mul_f32_e32 v134, v134, v178
	v_mul_f32_e32 v135, v135, v179
	v_cvt_pk_bf16_f32 v136, v132, v133
	v_cvt_pk_bf16_f32 v137, v134, v135
	v_add_u32_e32 v165, 0x61000, v164
	global_store_dwordx2 v165, v[136:137], s[34:35] offset:2056
	v_cndmask_b32_e64 v180, v72, v88, s[40:41]
	v_cndmask_b32_e64 v181, v72, v88, s[42:43]
	v_cndmask_b32_e64 v182, v73, v89, s[40:41]
	v_cndmask_b32_e64 v183, v73, v89, s[42:43]
	v_cndmask_b32_e64 v184, v74, v90, s[40:41]
	v_cndmask_b32_e64 v185, v74, v90, s[42:43]
	v_cndmask_b32_e64 v186, v75, v91, s[40:41]
	v_cndmask_b32_e64 v187, v75, v91, s[42:43]
	v_mov_b32_e32 v172, v214
	v_mov_b32_e32 v173, v215
	v_mov_b32_e32 v174, v216
	v_mov_b32_e32 v175, v217
	v_fmac_f32_dpp v172, v180, v202 row_ror:2 row_mask:0xf bank_mask:0xf
	v_fmac_f32_dpp v173, v182, v203 row_ror:2 row_mask:0xf bank_mask:0xf
	v_fmac_f32_dpp v174, v184, v204 row_ror:2 row_mask:0xf bank_mask:0xf
	v_fmac_f32_dpp v175, v186, v205 row_ror:2 row_mask:0xf bank_mask:0xf
	v_fmac_f32_dpp v172, v181, v206 row_ror:1 row_mask:0xf bank_mask:0xf
	v_fmac_f32_dpp v173, v183, v207 row_ror:1 row_mask:0xf bank_mask:0xf
	v_fmac_f32_dpp v174, v185, v208 row_ror:1 row_mask:0xf bank_mask:0xf
	v_fmac_f32_dpp v175, v187, v209 row_ror:1 row_mask:0xf bank_mask:0xf
	v_fmac_f32_e32 v172, v72, v210
	v_fmac_f32_e32 v173, v73, v211
	v_fmac_f32_e32 v174, v74, v212
	v_fmac_f32_e32 v175, v75, v213
	v_cndmask_b32_e64 v180, v68, v84, s[40:41]
	v_cndmask_b32_e64 v181, v68, v84, s[42:43]
	v_cndmask_b32_e64 v182, v69, v85, s[40:41]
	v_cndmask_b32_e64 v183, v69, v85, s[42:43]
	v_cndmask_b32_e64 v184, v70, v86, s[40:41]
	v_cndmask_b32_e64 v185, v70, v86, s[42:43]
	v_cndmask_b32_e64 v186, v71, v87, s[40:41]
	v_cndmask_b32_e64 v187, v71, v87, s[42:43]
	v_mov_b32_e32 v176, v230
	v_mov_b32_e32 v177, v231
	v_mov_b32_e32 v178, v232
	v_mov_b32_e32 v179, v233
	v_fmac_f32_dpp v176, v180, v218 row_ror:2 row_mask:0xf bank_mask:0xf
	v_fmac_f32_dpp v177, v182, v219 row_ror:2 row_mask:0xf bank_mask:0xf
	v_fmac_f32_dpp v178, v184, v220 row_ror:2 row_mask:0xf bank_mask:0xf
	v_fmac_f32_dpp v179, v186, v221 row_ror:2 row_mask:0xf bank_mask:0xf
	v_fmac_f32_dpp v176, v181, v222 row_ror:1 row_mask:0xf bank_mask:0xf
	v_fmac_f32_dpp v177, v183, v223 row_ror:1 row_mask:0xf bank_mask:0xf
	v_fmac_f32_dpp v178, v185, v224 row_ror:1 row_mask:0xf bank_mask:0xf
	v_fmac_f32_dpp v179, v187, v225 row_ror:1 row_mask:0xf bank_mask:0xf
	v_fmac_f32_e32 v176, v68, v226
	v_fmac_f32_e32 v177, v69, v227
	v_fmac_f32_e32 v178, v70, v228
	v_fmac_f32_e32 v179, v71, v229
	v_mul_f32_e32 v132, 0xbfb8aa3b, v172
	v_mul_f32_e32 v133, 0xbfb8aa3b, v173
	v_mul_f32_e32 v134, 0xbfb8aa3b, v174
	v_mul_f32_e32 v135, 0xbfb8aa3b, v175
	v_exp_f32_e32 v132, v132
	v_exp_f32_e32 v133, v133
	v_exp_f32_e32 v134, v134
	v_exp_f32_e32 v135, v135
	v_add_f32_e32 v132, 1.0, v132
	v_add_f32_e32 v133, 1.0, v133
	v_add_f32_e32 v134, 1.0, v134
	v_add_f32_e32 v135, 1.0, v135
	v_rcp_f32_e32 v132, v132
	v_rcp_f32_e32 v133, v133
	v_rcp_f32_e32 v134, v134
	v_rcp_f32_e32 v135, v135
	v_mul_f32_e32 v132, v172, v132
	v_mul_f32_e32 v133, v173, v133
	v_mul_f32_e32 v134, v174, v134
	v_mul_f32_e32 v135, v175, v135
	v_mul_f32_e32 v132, v132, v176
	v_mul_f32_e32 v133, v133, v177
	v_mul_f32_e32 v134, v134, v178
	v_mul_f32_e32 v135, v135, v179
	v_cvt_pk_bf16_f32 v138, v132, v133
	v_cvt_pk_bf16_f32 v139, v134, v135
	v_add_u32_e32 v165, 0x91800, v164
	global_store_dwordx2 v165, v[138:139], s[34:35] offset:2056
	v_cndmask_b32_e64 v180, v48, v31, s[40:41]
	v_cndmask_b32_e64 v181, v48, v31, s[42:43]
	v_cndmask_b32_e64 v182, v49, v31, s[40:41]
	v_cndmask_b32_e64 v183, v49, v31, s[42:43]
	v_cndmask_b32_e64 v184, v50, v31, s[40:41]
	v_cndmask_b32_e64 v185, v50, v31, s[42:43]
	v_cndmask_b32_e64 v186, v51, v31, s[40:41]
	v_cndmask_b32_e64 v187, v51, v31, s[42:43]
	v_mov_b32_e32 v172, v214
	v_mov_b32_e32 v173, v215
	v_mov_b32_e32 v174, v216
	v_mov_b32_e32 v175, v217
	v_fmac_f32_dpp v172, v180, v202 row_ror:2 row_mask:0xf bank_mask:0xf
	v_fmac_f32_dpp v173, v182, v203 row_ror:2 row_mask:0xf bank_mask:0xf
	v_fmac_f32_dpp v174, v184, v204 row_ror:2 row_mask:0xf bank_mask:0xf
	v_fmac_f32_dpp v175, v186, v205 row_ror:2 row_mask:0xf bank_mask:0xf
	v_fmac_f32_dpp v172, v181, v206 row_ror:1 row_mask:0xf bank_mask:0xf
	v_fmac_f32_dpp v173, v183, v207 row_ror:1 row_mask:0xf bank_mask:0xf
	v_fmac_f32_dpp v174, v185, v208 row_ror:1 row_mask:0xf bank_mask:0xf
	v_fmac_f32_dpp v175, v187, v209 row_ror:1 row_mask:0xf bank_mask:0xf
	v_fmac_f32_e32 v172, v48, v210
	v_fmac_f32_e32 v173, v49, v211
	v_fmac_f32_e32 v174, v50, v212
	v_fmac_f32_e32 v175, v51, v213
	v_cndmask_b32_e64 v180, v40, v31, s[40:41]
	v_cndmask_b32_e64 v181, v40, v31, s[42:43]
	v_cndmask_b32_e64 v182, v41, v31, s[40:41]
	v_cndmask_b32_e64 v183, v41, v31, s[42:43]
	v_cndmask_b32_e64 v184, v42, v31, s[40:41]
	v_cndmask_b32_e64 v185, v42, v31, s[42:43]
	v_cndmask_b32_e64 v186, v43, v31, s[40:41]
	v_cndmask_b32_e64 v187, v43, v31, s[42:43]
	v_mov_b32_e32 v176, v230
	v_mov_b32_e32 v177, v231
	v_mov_b32_e32 v178, v232
	v_mov_b32_e32 v179, v233
	v_fmac_f32_dpp v176, v180, v218 row_ror:2 row_mask:0xf bank_mask:0xf
	v_fmac_f32_dpp v177, v182, v219 row_ror:2 row_mask:0xf bank_mask:0xf
	v_fmac_f32_dpp v178, v184, v220 row_ror:2 row_mask:0xf bank_mask:0xf
	v_fmac_f32_dpp v179, v186, v221 row_ror:2 row_mask:0xf bank_mask:0xf
	v_fmac_f32_dpp v176, v181, v222 row_ror:1 row_mask:0xf bank_mask:0xf
	v_fmac_f32_dpp v177, v183, v223 row_ror:1 row_mask:0xf bank_mask:0xf
	v_fmac_f32_dpp v178, v185, v224 row_ror:1 row_mask:0xf bank_mask:0xf
	v_fmac_f32_dpp v179, v187, v225 row_ror:1 row_mask:0xf bank_mask:0xf
	v_fmac_f32_e32 v176, v40, v226
	v_fmac_f32_e32 v177, v41, v227
	v_fmac_f32_e32 v178, v42, v228
	v_fmac_f32_e32 v179, v43, v229
	v_mul_f32_e32 v132, 0xbfb8aa3b, v172
	v_mul_f32_e32 v133, 0xbfb8aa3b, v173
	v_mul_f32_e32 v134, 0xbfb8aa3b, v174
	v_mul_f32_e32 v135, 0xbfb8aa3b, v175
	v_exp_f32_e32 v132, v132
	v_exp_f32_e32 v133, v133
	v_exp_f32_e32 v134, v134
	v_exp_f32_e32 v135, v135
	v_add_f32_e32 v132, 1.0, v132
	v_add_f32_e32 v133, 1.0, v133
	v_add_f32_e32 v134, 1.0, v134
	v_add_f32_e32 v135, 1.0, v135
	v_rcp_f32_e32 v132, v132
	v_rcp_f32_e32 v133, v133
	v_rcp_f32_e32 v134, v134
	v_rcp_f32_e32 v135, v135
	v_mul_f32_e32 v132, v172, v132
	v_mul_f32_e32 v133, v173, v133
	v_mul_f32_e32 v134, v174, v134
	v_mul_f32_e32 v135, v175, v135
	v_mul_f32_e32 v132, v132, v176
	v_mul_f32_e32 v133, v133, v177
	v_mul_f32_e32 v134, v134, v178
	v_mul_f32_e32 v135, v135, v179
	v_cvt_pk_bf16_f32 v136, v132, v133
	v_cvt_pk_bf16_f32 v137, v134, v135
	v_add_u32_e32 v165, 0x184000, v164
	s_and_saveexec_b64 s[0:1], s[44:45]
	global_store_dwordx2 v165, v[136:137], s[34:35] offset:2056
	s_or_b64 exec, exec, s[0:1]
	v_cndmask_b32_e64 v180, v44, v48, s[40:41]
	v_cndmask_b32_e64 v181, v44, v48, s[42:43]
	v_cndmask_b32_e64 v182, v45, v49, s[40:41]
	v_cndmask_b32_e64 v183, v45, v49, s[42:43]
	v_cndmask_b32_e64 v184, v46, v50, s[40:41]
	v_cndmask_b32_e64 v185, v46, v50, s[42:43]
	v_cndmask_b32_e64 v186, v47, v51, s[40:41]
	v_cndmask_b32_e64 v187, v47, v51, s[42:43]
	v_mov_b32_e32 v172, v214
	v_mov_b32_e32 v173, v215
	v_mov_b32_e32 v174, v216
	v_mov_b32_e32 v175, v217
	v_fmac_f32_dpp v172, v180, v202 row_ror:2 row_mask:0xf bank_mask:0xf
	v_fmac_f32_dpp v173, v182, v203 row_ror:2 row_mask:0xf bank_mask:0xf
	v_fmac_f32_dpp v174, v184, v204 row_ror:2 row_mask:0xf bank_mask:0xf
	v_fmac_f32_dpp v175, v186, v205 row_ror:2 row_mask:0xf bank_mask:0xf
	v_fmac_f32_dpp v172, v181, v206 row_ror:1 row_mask:0xf bank_mask:0xf
	v_fmac_f32_dpp v173, v183, v207 row_ror:1 row_mask:0xf bank_mask:0xf
	v_fmac_f32_dpp v174, v185, v208 row_ror:1 row_mask:0xf bank_mask:0xf
	v_fmac_f32_dpp v175, v187, v209 row_ror:1 row_mask:0xf bank_mask:0xf
	v_fmac_f32_e32 v172, v44, v210
	v_fmac_f32_e32 v173, v45, v211
	v_fmac_f32_e32 v174, v46, v212
	v_fmac_f32_e32 v175, v47, v213
	v_cndmask_b32_e64 v180, v36, v40, s[40:41]
	v_cndmask_b32_e64 v181, v36, v40, s[42:43]
	v_cndmask_b32_e64 v182, v37, v41, s[40:41]
	v_cndmask_b32_e64 v183, v37, v41, s[42:43]
	v_cndmask_b32_e64 v184, v38, v42, s[40:41]
	v_cndmask_b32_e64 v185, v38, v42, s[42:43]
	v_cndmask_b32_e64 v186, v39, v43, s[40:41]
	v_cndmask_b32_e64 v187, v39, v43, s[42:43]
	v_mov_b32_e32 v176, v230
	v_mov_b32_e32 v177, v231
	v_mov_b32_e32 v178, v232
	v_mov_b32_e32 v179, v233
	v_fmac_f32_dpp v176, v180, v218 row_ror:2 row_mask:0xf bank_mask:0xf
	v_fmac_f32_dpp v177, v182, v219 row_ror:2 row_mask:0xf bank_mask:0xf
	v_fmac_f32_dpp v178, v184, v220 row_ror:2 row_mask:0xf bank_mask:0xf
	v_fmac_f32_dpp v179, v186, v221 row_ror:2 row_mask:0xf bank_mask:0xf
	v_fmac_f32_dpp v176, v181, v222 row_ror:1 row_mask:0xf bank_mask:0xf
	v_fmac_f32_dpp v177, v183, v223 row_ror:1 row_mask:0xf bank_mask:0xf
	v_fmac_f32_dpp v178, v185, v224 row_ror:1 row_mask:0xf bank_mask:0xf
	v_fmac_f32_dpp v179, v187, v225 row_ror:1 row_mask:0xf bank_mask:0xf
	v_fmac_f32_e32 v176, v36, v226
	v_fmac_f32_e32 v177, v37, v227
	v_fmac_f32_e32 v178, v38, v228
	v_fmac_f32_e32 v179, v39, v229
	v_mul_f32_e32 v132, 0xbfb8aa3b, v172
	v_mul_f32_e32 v133, 0xbfb8aa3b, v173
	v_mul_f32_e32 v134, 0xbfb8aa3b, v174
	v_mul_f32_e32 v135, 0xbfb8aa3b, v175
	v_exp_f32_e32 v132, v132
	v_exp_f32_e32 v133, v133
	v_exp_f32_e32 v134, v134
	v_exp_f32_e32 v135, v135
	v_add_f32_e32 v132, 1.0, v132
	v_add_f32_e32 v133, 1.0, v133
	v_add_f32_e32 v134, 1.0, v134
	v_add_f32_e32 v135, 1.0, v135
	v_rcp_f32_e32 v132, v132
	v_rcp_f32_e32 v133, v133
	v_rcp_f32_e32 v134, v134
	v_rcp_f32_e32 v135, v135
	v_mul_f32_e32 v132, v172, v132
	v_mul_f32_e32 v133, v173, v133
	v_mul_f32_e32 v134, v174, v134
	v_mul_f32_e32 v135, v175, v135
	v_mul_f32_e32 v132, v132, v176
	v_mul_f32_e32 v133, v133, v177
	v_mul_f32_e32 v134, v134, v178
	v_mul_f32_e32 v135, v135, v179
	v_cvt_pk_bf16_f32 v138, v132, v133
	v_cvt_pk_bf16_f32 v139, v134, v135
	v_add_u32_e32 v165, 0x1b4800, v164
	global_store_dwordx2 v165, v[138:139], s[34:35] offset:2056
	v_cndmask_b32_e64 v180, v20, v44, s[40:41]
	v_cndmask_b32_e64 v181, v20, v44, s[42:43]
	v_cndmask_b32_e64 v182, v21, v45, s[40:41]
	v_cndmask_b32_e64 v183, v21, v45, s[42:43]
	v_cndmask_b32_e64 v184, v22, v46, s[40:41]
	v_cndmask_b32_e64 v185, v22, v46, s[42:43]
	v_cndmask_b32_e64 v186, v23, v47, s[40:41]
	v_cndmask_b32_e64 v187, v23, v47, s[42:43]
	v_mov_b32_e32 v172, v214
	v_mov_b32_e32 v173, v215
	v_mov_b32_e32 v174, v216
	v_mov_b32_e32 v175, v217
	v_fmac_f32_dpp v172, v180, v202 row_ror:2 row_mask:0xf bank_mask:0xf
	v_fmac_f32_dpp v173, v182, v203 row_ror:2 row_mask:0xf bank_mask:0xf
	v_fmac_f32_dpp v174, v184, v204 row_ror:2 row_mask:0xf bank_mask:0xf
	v_fmac_f32_dpp v175, v186, v205 row_ror:2 row_mask:0xf bank_mask:0xf
	v_fmac_f32_dpp v172, v181, v206 row_ror:1 row_mask:0xf bank_mask:0xf
	v_fmac_f32_dpp v173, v183, v207 row_ror:1 row_mask:0xf bank_mask:0xf
	v_fmac_f32_dpp v174, v185, v208 row_ror:1 row_mask:0xf bank_mask:0xf
	v_fmac_f32_dpp v175, v187, v209 row_ror:1 row_mask:0xf bank_mask:0xf
	v_fmac_f32_e32 v172, v20, v210
	v_fmac_f32_e32 v173, v21, v211
	v_fmac_f32_e32 v174, v22, v212
	v_fmac_f32_e32 v175, v23, v213
	v_cndmask_b32_e64 v180, v16, v36, s[40:41]
	v_cndmask_b32_e64 v181, v16, v36, s[42:43]
	v_cndmask_b32_e64 v182, v17, v37, s[40:41]
	v_cndmask_b32_e64 v183, v17, v37, s[42:43]
	v_cndmask_b32_e64 v184, v18, v38, s[40:41]
	v_cndmask_b32_e64 v185, v18, v38, s[42:43]
	v_cndmask_b32_e64 v186, v19, v39, s[40:41]
	v_cndmask_b32_e64 v187, v19, v39, s[42:43]
	v_mov_b32_e32 v176, v230
	v_mov_b32_e32 v177, v231
	v_mov_b32_e32 v178, v232
	v_mov_b32_e32 v179, v233
	v_fmac_f32_dpp v176, v180, v218 row_ror:2 row_mask:0xf bank_mask:0xf
	v_fmac_f32_dpp v177, v182, v219 row_ror:2 row_mask:0xf bank_mask:0xf
	v_fmac_f32_dpp v178, v184, v220 row_ror:2 row_mask:0xf bank_mask:0xf
	v_fmac_f32_dpp v179, v186, v221 row_ror:2 row_mask:0xf bank_mask:0xf
	v_fmac_f32_dpp v176, v181, v222 row_ror:1 row_mask:0xf bank_mask:0xf
	v_fmac_f32_dpp v177, v183, v223 row_ror:1 row_mask:0xf bank_mask:0xf
	v_fmac_f32_dpp v178, v185, v224 row_ror:1 row_mask:0xf bank_mask:0xf
	v_fmac_f32_dpp v179, v187, v225 row_ror:1 row_mask:0xf bank_mask:0xf
	v_fmac_f32_e32 v176, v16, v226
	v_fmac_f32_e32 v177, v17, v227
	v_fmac_f32_e32 v178, v18, v228
	v_fmac_f32_e32 v179, v19, v229
	v_mul_f32_e32 v132, 0xbfb8aa3b, v172
	v_mul_f32_e32 v133, 0xbfb8aa3b, v173
	v_mul_f32_e32 v134, 0xbfb8aa3b, v174
	v_mul_f32_e32 v135, 0xbfb8aa3b, v175
	v_exp_f32_e32 v132, v132
	v_exp_f32_e32 v133, v133
	v_exp_f32_e32 v134, v134
	v_exp_f32_e32 v135, v135
	v_add_f32_e32 v132, 1.0, v132
	v_add_f32_e32 v133, 1.0, v133
	v_add_f32_e32 v134, 1.0, v134
	v_add_f32_e32 v135, 1.0, v135
	v_rcp_f32_e32 v132, v132
	v_rcp_f32_e32 v133, v133
	v_rcp_f32_e32 v134, v134
	v_rcp_f32_e32 v135, v135
	v_mul_f32_e32 v132, v172, v132
	v_mul_f32_e32 v133, v173, v133
	v_mul_f32_e32 v134, v174, v134
	v_mul_f32_e32 v135, v175, v135
	v_mul_f32_e32 v132, v132, v176
	v_mul_f32_e32 v133, v133, v177
	v_mul_f32_e32 v134, v134, v178
	v_mul_f32_e32 v135, v135, v179
	v_cvt_pk_bf16_f32 v136, v132, v133
	v_cvt_pk_bf16_f32 v137, v134, v135
	v_add_u32_e32 v165, 0x1e5000, v164
	global_store_dwordx2 v165, v[136:137], s[34:35] offset:2056
	v_cndmask_b32_e64 v180, v4, v20, s[40:41]
	v_cndmask_b32_e64 v181, v4, v20, s[42:43]
	v_cndmask_b32_e64 v182, v5, v21, s[40:41]
	v_cndmask_b32_e64 v183, v5, v21, s[42:43]
	v_cndmask_b32_e64 v184, v6, v22, s[40:41]
	v_cndmask_b32_e64 v185, v6, v22, s[42:43]
	v_cndmask_b32_e64 v186, v7, v23, s[40:41]
	v_cndmask_b32_e64 v187, v7, v23, s[42:43]
	v_mov_b32_e32 v172, v214
	v_mov_b32_e32 v173, v215
	v_mov_b32_e32 v174, v216
	v_mov_b32_e32 v175, v217
	v_fmac_f32_dpp v172, v180, v202 row_ror:2 row_mask:0xf bank_mask:0xf
	v_fmac_f32_dpp v173, v182, v203 row_ror:2 row_mask:0xf bank_mask:0xf
	v_fmac_f32_dpp v174, v184, v204 row_ror:2 row_mask:0xf bank_mask:0xf
	v_fmac_f32_dpp v175, v186, v205 row_ror:2 row_mask:0xf bank_mask:0xf
	v_fmac_f32_dpp v172, v181, v206 row_ror:1 row_mask:0xf bank_mask:0xf
	v_fmac_f32_dpp v173, v183, v207 row_ror:1 row_mask:0xf bank_mask:0xf
	v_fmac_f32_dpp v174, v185, v208 row_ror:1 row_mask:0xf bank_mask:0xf
	v_fmac_f32_dpp v175, v187, v209 row_ror:1 row_mask:0xf bank_mask:0xf
	v_fmac_f32_e32 v172, v4, v210
	v_fmac_f32_e32 v173, v5, v211
	v_fmac_f32_e32 v174, v6, v212
	v_fmac_f32_e32 v175, v7, v213
	v_cndmask_b32_e64 v180, v0, v16, s[40:41]
	v_cndmask_b32_e64 v181, v0, v16, s[42:43]
	v_cndmask_b32_e64 v182, v1, v17, s[40:41]
	v_cndmask_b32_e64 v183, v1, v17, s[42:43]
	v_cndmask_b32_e64 v184, v2, v18, s[40:41]
	v_cndmask_b32_e64 v185, v2, v18, s[42:43]
	v_cndmask_b32_e64 v186, v3, v19, s[40:41]
	v_cndmask_b32_e64 v187, v3, v19, s[42:43]
	v_mov_b32_e32 v176, v230
	v_mov_b32_e32 v177, v231
	v_mov_b32_e32 v178, v232
	v_mov_b32_e32 v179, v233
	v_fmac_f32_dpp v176, v180, v218 row_ror:2 row_mask:0xf bank_mask:0xf
	v_fmac_f32_dpp v177, v182, v219 row_ror:2 row_mask:0xf bank_mask:0xf
	v_fmac_f32_dpp v178, v184, v220 row_ror:2 row_mask:0xf bank_mask:0xf
	v_fmac_f32_dpp v179, v186, v221 row_ror:2 row_mask:0xf bank_mask:0xf
	v_fmac_f32_dpp v176, v181, v222 row_ror:1 row_mask:0xf bank_mask:0xf
	v_fmac_f32_dpp v177, v183, v223 row_ror:1 row_mask:0xf bank_mask:0xf
	v_fmac_f32_dpp v178, v185, v224 row_ror:1 row_mask:0xf bank_mask:0xf
	v_fmac_f32_dpp v179, v187, v225 row_ror:1 row_mask:0xf bank_mask:0xf
	v_fmac_f32_e32 v176, v0, v226
	v_fmac_f32_e32 v177, v1, v227
	v_fmac_f32_e32 v178, v2, v228
	v_fmac_f32_e32 v179, v3, v229
	v_mul_f32_e32 v132, 0xbfb8aa3b, v172
	v_mul_f32_e32 v133, 0xbfb8aa3b, v173
	v_mul_f32_e32 v134, 0xbfb8aa3b, v174
	v_mul_f32_e32 v135, 0xbfb8aa3b, v175
	v_exp_f32_e32 v132, v132
	v_exp_f32_e32 v133, v133
	v_exp_f32_e32 v134, v134
	v_exp_f32_e32 v135, v135
	v_add_f32_e32 v132, 1.0, v132
	v_add_f32_e32 v133, 1.0, v133
	v_add_f32_e32 v134, 1.0, v134
	v_add_f32_e32 v135, 1.0, v135
	v_rcp_f32_e32 v132, v132
	v_rcp_f32_e32 v133, v133
	v_rcp_f32_e32 v134, v134
	v_rcp_f32_e32 v135, v135
	v_mul_f32_e32 v132, v172, v132
	v_mul_f32_e32 v133, v173, v133
	v_mul_f32_e32 v134, v174, v134
	v_mul_f32_e32 v135, v175, v135
	v_mul_f32_e32 v132, v132, v176
	v_mul_f32_e32 v133, v133, v177
	v_mul_f32_e32 v134, v134, v178
	v_mul_f32_e32 v135, v135, v179
	v_cvt_pk_bf16_f32 v138, v132, v133
	v_cvt_pk_bf16_f32 v139, v134, v135
	v_add_u32_e32 v165, 0x215800, v164
	global_store_dwordx2 v165, v[138:139], s[34:35] offset:2056
	s_and_b64 vcc, exec, s[38:39]
	s_mov_b64 s[0:1], -1
	s_cbranch_vccnz .LBB0_217
	s_andn2_b64 vcc, exec, s[4:5]
	s_cbranch_vccnz .LBB0_216
	s_barrier
	s_branch .LBB0_216
